# phase +8 LayerNorm: next row's x loads issued one row ahead (software-pipelined), counted vmcnt(4) at the loop top
# speedup vs baseline: 1.0129x; 1.0025x over previous
.LBB0_1229:
	s_andn2_b64 vcc, exec, s[0:1]
	s_cbranch_vccnz .LBB0_1408
	v_readlane_b32 s10, v243, 26
	v_readlane_b32 s11, v243, 27
	s_mov_b64 s[0:1], -1
	s_and_b64 vcc, exec, s[10:11]
	s_cbranch_vccz .LBB0_1345
	v_readlane_b32 s0, v239, 48
	v_mov_b32_e32 v2, v0
	v_readlane_b32 s18, v243, 28
	v_mov_b32_e32 v3, s0
	ds_read2_b64 v[4:7], v3 offset1:1
	v_readlane_b32 s0, v238, 14
	v_readlane_b32 s1, v238, 15
	s_cmp_lg_u32 s0, 3
	v_readlane_b32 s19, v243, 29
	s_cselect_b64 s[10:11], -1, 0
	s_waitcnt lgkmcnt(0)
	v_readfirstlane_b32 s0, v5
	v_readfirstlane_b32 s1, v4
	v_readfirstlane_b32 s14, v7
	s_andn2_b64 vcc, exec, s[18:19]
	v_readfirstlane_b32 s15, v6
	s_cbranch_vccnz .LBB0_1250
	v_and_b32_e32 v4, 63, v2
	v_and_b32_e32 v2, 64, v203
	v_add_u32_e32 v2, 64, v2
	v_xor_b32_e32 v3, 1, v203
	v_cmp_lt_i32_e32 vcc, v3, v2
	v_readlane_b32 s18, v238, 14
	v_readlane_b32 s19, v238, 15
	v_cndmask_b32_e32 v3, v203, v3, vcc
	v_lshlrev_b32_e32 v60, 2, v3
	v_xor_b32_e32 v3, 2, v203
	v_cmp_lt_i32_e32 vcc, v3, v2
	s_lshl_b32 s90, s18, 11
	s_lshl_b64 s[18:19], s[90:91], 2
	v_cndmask_b32_e32 v3, v203, v3, vcc
	v_lshlrev_b32_e32 v61, 2, v3
	v_xor_b32_e32 v3, 4, v203
	v_cmp_lt_i32_e32 vcc, v3, v2
	s_add_u32 s20, s15, s18
	s_addc_u32 s21, s14, s19
	v_cndmask_b32_e32 v3, v203, v3, vcc
	v_lshlrev_b32_e32 v62, 2, v3
	v_xor_b32_e32 v3, 8, v203
	v_cmp_lt_i32_e32 vcc, v3, v2
	s_add_u32 s14, s1, s18
	v_lshlrev_b32_e32 v172, 5, v4
	v_cndmask_b32_e32 v3, v203, v3, vcc
	v_lshlrev_b32_e32 v63, 2, v3
	v_xor_b32_e32 v3, 16, v203
	v_cmp_lt_i32_e32 vcc, v3, v2
	s_addc_u32 s15, s0, s19
	v_readlane_b32 s0, v240, 21
	v_cndmask_b32_e32 v3, v203, v3, vcc
	v_lshlrev_b32_e32 v64, 2, v3
	v_xor_b32_e32 v3, 32, v203
	v_cmp_lt_i32_e32 vcc, v3, v2
	v_readlane_b32 s1, v240, 22
	v_lshl_add_u64 v[10:11], s[14:15], 0, v[172:173]
	v_cndmask_b32_e32 v2, v203, v3, vcc
	v_lshlrev_b32_e32 v65, 2, v2
	v_or_b32_e32 v2, 0x1000, v172
	v_mov_b32_e32 v3, v173
	v_lshl_add_u64 v[14:15], s[14:15], 0, v[2:3]
	v_lshl_add_u64 v[16:17], s[20:21], 0, v[2:3]
	v_or_b32_e32 v2, 0x1800, v172
	v_lshl_add_u64 v[18:19], s[14:15], 0, v[2:3]
	v_lshl_add_u64 v[20:21], s[20:21], 0, v[2:3]
	v_lshlrev_b32_e32 v2, 4, v4
	v_lshl_add_u64 v[22:23], s[0:1], 0, v[2:3]
	v_readlane_b32 s0, v240, 27
	v_readlane_b32 s1, v240, 28
	v_lshl_add_u64 v[12:13], s[20:21], 0, v[172:173]
	s_nop 0
	v_lshl_add_u64 v[24:25], s[0:1], 0, v[172:173]
	v_readlane_b32 s0, v240, 25
	s_mov_b32 s14, s0
	v_readlane_b32 s1, v240, 26
	global_load_dwordx4 v[112:115], v[10:11], off
	global_load_dwordx4 v[116:119], v[12:13], off
	global_load_dwordx4 v[120:123], v[10:11], off offset:16
	global_load_dwordx4 v[124:127], v[12:13], off offset:16
	global_load_dwordx4 v[128:131], v[10:11], off offset:2048
	global_load_dwordx4 v[132:135], v[12:13], off offset:2048
	global_load_dwordx4 v[136:139], v[10:11], off offset:2064
	global_load_dwordx4 v[140:143], v[12:13], off offset:2064
	global_load_dwordx4 v[144:147], v[14:15], off
	global_load_dwordx4 v[148:151], v[16:17], off
	global_load_dwordx4 v[152:155], v[14:15], off offset:16
	global_load_dwordx4 v[156:159], v[16:17], off offset:16
	global_load_dwordx4 v[160:163], v[20:21], off
	global_load_dwordx4 v[164:167], v[18:19], off
	global_load_dwordx4 v[204:207], v[18:19], off offset:16
	global_load_dwordx4 v[208:211], v[20:21], off offset:16
	global_load_dwordx4 v[212:215], v[22:23], off
	global_load_dwordx4 v[216:219], v[22:23], off offset:1024
	global_load_dwordx4 v[220:223], v[22:23], off offset:2048
	global_load_dwordx4 v[224:227], v[22:23], off offset:3072
	s_waitcnt vmcnt(0)
	s_branch .LBB0_1234

.LBB0_1234:
	s_waitcnt vmcnt(4)
	v_mov_b32_e32 v2, v212
	v_mov_b32_e32 v3, v213
	v_mov_b32_e32 v4, v214
	v_mov_b32_e32 v5, v215
	v_mov_b32_e32 v6, v216
	v_mov_b32_e32 v7, v217
	v_mov_b32_e32 v8, v218
	v_mov_b32_e32 v9, v219
	v_mov_b32_e32 v46, v220
	v_mov_b32_e32 v47, v221
	v_mov_b32_e32 v48, v222
	v_mov_b32_e32 v49, v223
	v_mov_b32_e32 v28, v224
	v_mov_b32_e32 v29, v225
	v_mov_b32_e32 v30, v226
	v_mov_b32_e32 v31, v227
	v_readlane_b32 s0, v240, 29
	s_add_i32 s0, s14, s0
	s_cmpk_lt_i32 s0, 0x1c00
	s_cbranch_scc0 .Llnpf_last
	v_readlane_b32 s0, v240, 23
	v_readlane_b32 s1, v240, 24
	s_nop 1
	v_lshl_add_u64 v[228:229], v[22:23], 0, s[0:1]
	global_load_dwordx4 v[212:215], v[228:229], off
	global_load_dwordx4 v[216:219], v[228:229], off offset:1024
	global_load_dwordx4 v[220:223], v[228:229], off offset:2048
	global_load_dwordx4 v[224:227], v[228:229], off offset:3072
.Llnpf_last:
	v_and_b32_e32 v59, 0xffff0000, v2
	v_lshlrev_b32_e32 v50, 16, v8
	v_and_b32_e32 v51, 0xffff0000, v8
	v_lshlrev_b32_e32 v52, 16, v9
	v_and_b32_e32 v53, 0xffff0000, v9
	v_lshlrev_b32_e32 v9, 16, v2
	v_lshlrev_b32_e32 v8, 16, v4
	v_and_b32_e32 v58, 0xffff0000, v4
	v_lshlrev_b32_e32 v67, 16, v3
	v_lshlrev_b32_e32 v66, 16, v5
	v_and_b32_e32 v69, 0xffff0000, v3
	v_and_b32_e32 v68, 0xffff0000, v5
	v_pk_add_f32 v[2:3], v[8:9], v[58:59]
	v_pk_add_f32 v[4:5], v[66:67], v[68:69]
	v_lshlrev_b32_e32 v55, 16, v7
	v_pk_add_f32 v[2:3], v[2:3], v[4:5]
	v_lshlrev_b32_e32 v54, 16, v6
	v_add_f32_e32 v3, 0, v3
	v_and_b32_e32 v57, 0xffff0000, v7
	v_and_b32_e32 v56, 0xffff0000, v6
	v_add_f32_e32 v43, v2, v3
	v_pk_add_f32 v[2:3], v[54:55], v[56:57]
	v_lshlrev_b32_e32 v38, 16, v46
	v_pk_add_f32 v[2:3], v[2:3], v[2:3] op_sel_hi:[0,1]
	v_and_b32_e32 v44, 0xffff0000, v46
	v_lshlrev_b32_e32 v40, 16, v47
	v_and_b32_e32 v42, 0xffff0000, v47
	v_add_f32_e32 v39, v50, v51
	v_add_f32_e32 v45, v52, v53
	v_mov_b32_e32 v41, v3
	v_pk_add_f32 v[4:5], v[38:39], v[44:45]
	v_pk_add_f32 v[2:3], v[40:41], v[42:43]
	v_lshlrev_b32_e32 v47, 16, v49
	v_lshlrev_b32_e32 v46, 16, v48
	v_and_b32_e32 v49, 0xffff0000, v49
	v_and_b32_e32 v48, 0xffff0000, v48
	v_pk_add_f32 v[2:3], v[4:5], v[2:3]
	v_pk_add_f32 v[4:5], v[46:47], v[48:49]
	v_lshlrev_b32_e32 v32, 16, v28
	v_and_b32_e32 v33, 0xffff0000, v28
	v_lshlrev_b32_e32 v26, 16, v29
	v_and_b32_e32 v27, 0xffff0000, v29
	v_pk_add_f32 v[2:3], v[2:3], v[2:3] op_sel_hi:[0,1]
	v_pk_add_f32 v[4:5], v[4:5], v[4:5] op_sel_hi:[0,1]
	v_lshlrev_b32_e32 v28, 16, v30
	v_and_b32_e32 v36, 0xffff0000, v30
	v_lshlrev_b32_e32 v30, 16, v31
	v_and_b32_e32 v34, 0xffff0000, v31
	v_add_f32_e32 v29, v32, v33
	v_add_f32_e32 v37, v26, v27
	v_mov_b32_e32 v31, v5
	v_mov_b32_e32 v35, v3
	v_pk_add_f32 v[6:7], v[28:29], v[36:37]
	v_pk_add_f32 v[2:3], v[30:31], v[34:35]
	s_nop 0
	v_pk_add_f32 v[2:3], v[6:7], v[2:3]
	s_nop 0
	v_add_f32_e32 v2, v2, v3
	s_waitcnt lgkmcnt(0)
	s_nop 1
	v_add_f32_dpp v2, v2, v2 quad_perm:[1,0,3,2] row_mask:0xf bank_mask:0xf
	s_nop 1
	v_add_f32_dpp v2, v2, v2 quad_perm:[2,3,0,1] row_mask:0xf bank_mask:0xf
	s_nop 1
	v_add_f32_dpp v2, v2, v2 row_half_mirror row_mask:0xf bank_mask:0xf
	s_nop 1
	v_add_f32_dpp v2, v2, v2 row_mirror row_mask:0xf bank_mask:0xf
	s_nop 1
	v_add_f32_dpp v2, v2, v2 row_bcast:15 row_mask:0xa bank_mask:0xf
	s_nop 1
	v_add_f32_dpp v2, v2, v2 row_bcast:31 row_mask:0xc bank_mask:0xf
	s_nop 1
	v_readlane_b32 s100, v2, 63
	v_mov_b32_e32 v29, s100
	v_fmac_f32_e32 v59, 0xba000000, v29
	v_fmac_f32_e32 v9, 0xba000000, v29
	v_fmac_f32_e32 v58, 0xba000000, v29
	v_fmac_f32_e32 v8, 0xba000000, v29
	v_mov_b32_e32 v6, v8
	v_mov_b32_e32 v2, v9
	v_mov_b32_e32 v4, v9
	v_mov_b32_e32 v5, v8
	v_mov_b32_e32 v8, v59
	v_mov_b32_e32 v9, v58
	v_fmac_f32_e32 v69, 0xba000000, v29
	v_fmac_f32_e32 v67, 0xba000000, v29
	v_fmac_f32_e32 v68, 0xba000000, v29
	v_fmac_f32_e32 v66, 0xba000000, v29
	v_pk_mul_f32 v[8:9], v[8:9], v[8:9]
	v_mov_b32_e32 v7, v58
	v_mov_b32_e32 v3, v59
	v_pk_fma_f32 v[58:59], v[4:5], v[4:5], v[8:9]
	v_mov_b32_e32 v8, v66
	v_mov_b32_e32 v4, v67
	v_mov_b32_e32 v70, v67
	v_mov_b32_e32 v71, v66
	v_mov_b32_e32 v66, v69
	v_mov_b32_e32 v67, v68
	v_pk_mul_f32 v[66:67], v[66:67], v[66:67]
	v_fmac_f32_e32 v57, 0xba000000, v29
	v_pk_fma_f32 v[66:67], v[70:71], v[70:71], v[66:67]
	v_fmac_f32_e32 v55, 0xba000000, v29
	v_fmac_f32_e32 v56, 0xba000000, v29
	v_fmac_f32_e32 v54, 0xba000000, v29
	v_mov_b32_e32 v9, v68
	v_mov_b32_e32 v5, v69
	v_pk_add_f32 v[58:59], v[58:59], v[66:67]
	v_mov_b32_e32 v66, v55
	v_mov_b32_e32 v67, v57
	v_mov_b32_e32 v68, v54
	v_mov_b32_e32 v69, v56
	v_pk_add_f32 v[58:59], v[58:59], v[58:59] op_sel_hi:[0,1]
	v_pk_mul_f32 v[66:67], v[66:67], v[66:67]
	v_pk_mul_f32 v[68:69], v[68:69], v[68:69]
	v_fmac_f32_e32 v50, 0xba000000, v29
	v_pk_mov_b32 v[70:71], v[68:69], v[66:67] op_sel:[1,0]
	v_mov_b32_e32 v69, v67
	v_fmac_f32_e32 v52, 0xba000000, v29
	v_fmac_f32_e32 v51, 0xba000000, v29
	v_mul_f32_e32 v58, v50, v50
	v_pk_add_f32 v[66:67], v[70:71], v[68:69]
	v_fmac_f32_e32 v53, 0xba000000, v29
	v_pk_fma_f32 v[68:69], v[50:51], v[50:51], v[58:59] op_sel_hi:[1,1,0]
	v_mul_f32_e32 v58, v52, v52
	v_pk_add_f32 v[66:67], v[66:67], v[66:67] op_sel_hi:[0,1]
	v_pk_fma_f32 v[70:71], v[52:53], v[52:53], v[58:59] op_sel_hi:[1,1,0]
	v_fmac_f32_e32 v42, 0xba000000, v29
	v_fmac_f32_e32 v40, 0xba000000, v29
	v_fmac_f32_e32 v44, 0xba000000, v29
	v_fmac_f32_e32 v38, 0xba000000, v29
	v_mul_f32_e32 v68, v38, v38
	v_mul_f32_e32 v70, v44, v44
	v_mul_f32_e32 v66, v40, v40
	v_mul_f32_e32 v58, v42, v42
	v_pk_add_f32 v[68:69], v[68:69], v[70:71]
	v_pk_add_f32 v[58:59], v[66:67], v[58:59]
	v_fmac_f32_e32 v49, 0xba000000, v29
	v_fmac_f32_e32 v47, 0xba000000, v29
	v_fmac_f32_e32 v48, 0xba000000, v29
	v_fmac_f32_e32 v46, 0xba000000, v29
	v_pk_add_f32 v[58:59], v[68:69], v[58:59]
	v_mov_b32_e32 v66, v47
	v_mov_b32_e32 v67, v49
	v_mov_b32_e32 v68, v46
	v_mov_b32_e32 v69, v48
	v_pk_add_f32 v[58:59], v[58:59], v[58:59] op_sel_hi:[0,1]
	v_pk_mul_f32 v[66:67], v[66:67], v[66:67]
	v_pk_mul_f32 v[68:69], v[68:69], v[68:69]
	v_fmac_f32_e32 v32, 0xba000000, v29
	v_pk_mov_b32 v[70:71], v[68:69], v[66:67] op_sel:[1,0]
	v_mov_b32_e32 v69, v67
	v_fmac_f32_e32 v26, 0xba000000, v29
	v_fmac_f32_e32 v33, 0xba000000, v29
	v_mul_f32_e32 v58, v32, v32
	v_pk_add_f32 v[66:67], v[70:71], v[68:69]
	v_fmac_f32_e32 v27, 0xba000000, v29
	v_pk_fma_f32 v[68:69], v[32:33], v[32:33], v[58:59] op_sel_hi:[1,1,0]
	v_mul_f32_e32 v58, v26, v26
	v_pk_add_f32 v[66:67], v[66:67], v[66:67] op_sel_hi:[0,1]
	v_pk_fma_f32 v[70:71], v[26:27], v[26:27], v[58:59] op_sel_hi:[1,1,0]
	v_fmac_f32_e32 v34, 0xba000000, v29
	v_fmac_f32_e32 v30, 0xba000000, v29
	v_fmac_f32_e32 v36, 0xba000000, v29
	v_fmac_f32_e32 v28, 0xba000000, v29
	v_mul_f32_e32 v68, v28, v28
	v_mul_f32_e32 v70, v36, v36
	v_mul_f32_e32 v66, v30, v30
	v_mul_f32_e32 v58, v34, v34
	v_pk_add_f32 v[68:69], v[68:69], v[70:71]
	v_pk_add_f32 v[58:59], v[66:67], v[58:59]
	s_nop 0
	v_pk_add_f32 v[58:59], v[68:69], v[58:59]
	s_nop 0
	v_add_f32_e32 v29, v58, v59
	s_waitcnt lgkmcnt(0)
	s_nop 1
	v_add_f32_dpp v29, v29, v29 quad_perm:[1,0,3,2] row_mask:0xf bank_mask:0xf
	s_nop 1
	v_add_f32_dpp v29, v29, v29 quad_perm:[2,3,0,1] row_mask:0xf bank_mask:0xf
	s_nop 1
	v_add_f32_dpp v29, v29, v29 row_half_mirror row_mask:0xf bank_mask:0xf
	s_nop 1
	v_add_f32_dpp v29, v29, v29 row_mirror row_mask:0xf bank_mask:0xf
	s_nop 1
	v_add_f32_dpp v29, v29, v29 row_bcast:15 row_mask:0xa bank_mask:0xf
	s_nop 1
	v_add_f32_dpp v29, v29, v29 row_bcast:31 row_mask:0xc bank_mask:0xf
	s_nop 1
	v_readlane_b32 s100, v29, 63
	v_mov_b32_e32 v29, s100
	v_fmamk_f32 v29, v29, 0x3a000000, v171
	v_cmp_gt_f32_e32 vcc, s9, v29
	v_mul_f32_e32 v31, 0x4f800000, v29
	s_nop 0
	v_cndmask_b32_e32 v29, v29, v31, vcc
	v_sqrt_f32_e32 v31, v29
	s_nop 0
	v_add_u32_e32 v35, -1, v31
	v_fma_f32 v37, -v35, v31, v29
	v_cmp_ge_f32_e64 s[0:1], 0, v37
	v_add_u32_e32 v37, 1, v31
	s_nop 0
	v_cndmask_b32_e64 v35, v31, v35, s[0:1]
	v_fma_f32 v31, -v37, v31, v29
	v_cmp_lt_f32_e64 s[0:1], 0, v31
	s_nop 1
	v_cndmask_b32_e64 v31, v35, v37, s[0:1]
	v_mul_f32_e32 v35, 0x37800000, v31
	v_cndmask_b32_e32 v31, v31, v35, vcc
	v_cmp_class_f32_e32 vcc, v29, v200
	s_nop 1
	v_cndmask_b32_e32 v29, v31, v29, vcc
	v_div_scale_f32 v31, s[0:1], v29, v29, 1.0
	v_rcp_f32_e32 v35, v31
	s_mov_b64 s[0:1], -1
	v_fma_f32 v37, -v31, v35, 1.0
	v_fmac_f32_e32 v35, v37, v35
	v_div_scale_f32 v37, vcc, 1.0, v29, 1.0
	v_mul_f32_e32 v39, v37, v35
	v_fma_f32 v41, -v31, v39, v37
	v_fmac_f32_e32 v39, v41, v35
	v_fma_f32 v31, -v31, v39, v37
	v_div_fmas_f32 v31, v31, v35, v39
	v_div_fixup_f32 v58, v31, v29, 1.0
	v_pk_mul_f32 v[70:71], v[2:3], v[58:59] op_sel_hi:[1,0]
	v_pk_mul_f32 v[72:73], v[4:5], v[58:59] op_sel_hi:[1,0]
	s_nop 0
	s_nop 0
	v_pk_mul_f32 v[6:7], v[6:7], v[58:59] op_sel_hi:[1,0]
	v_pk_mul_f32 v[8:9], v[8:9], v[58:59] op_sel_hi:[1,0]
	s_and_b64 vcc, exec, s[10:11]
	s_nop 0
	v_pk_fma_f32 v[4:5], v[114:115], v[72:73], v[118:119]
	v_pk_fma_f32 v[2:3], v[112:113], v[70:71], v[116:117]
	s_nop 0
	s_nop 0
	s_nop 0
	v_pk_fma_f32 v[8:9], v[122:123], v[8:9], v[126:127]
	v_pk_fma_f32 v[6:7], v[120:121], v[6:7], v[124:125]
	s_cbranch_vccz .LBB0_1236
	v_add_co_u32_e32 v70, vcc, 0xd8900000, v22
	v_cvt_pk_bf16_f32 v66, v2, v3
	v_cvt_pk_bf16_f32 v67, v4, v5
	v_cvt_pk_bf16_f32 v68, v6, v7
	v_cvt_pk_bf16_f32 v69, v8, v9
	s_nop 1
	v_addc_co_u32_e32 v71, vcc, -1, v23, vcc
	global_store_dwordx4 v[70:71], v[66:69], off
	s_mov_b64 s[0:1], 0
